# attention queue: workgroups without scan waves fetch 8 consecutive units at once (one atomic by wave 0, broadcast through LDS, two barriers per round) so the 8 waves of a CU work on adjacent query til
# baseline (speedup 1.0000x reference)
.LBB0_440:
	v_readlane_b32 s98, v255, 3
	s_cmp_lt_u32 s98, 0x200
	s_cbranch_scc1 .Lq_single
	s_barrier
	s_cmp_lg_u32 s77, 0
	s_cbranch_scc1 .Lq_wait
	v_mov_b32_e32 v0, 0
	s_and_saveexec_b64 s[4:5], s[34:35]
	v_mov_b32_e32 v2, 8
	global_atomic_add v0, v[166:167], v2, off sc0
	s_waitcnt vmcnt(0)
	v_mov_b32_e32 v3, 0x4840
	ds_write_b32 v3, v0
	s_waitcnt lgkmcnt(0)
	s_or_b64 exec, exec, s[4:5]
.Lq_wait:
	s_barrier
	v_mov_b32_e32 v3, 0x4840
	ds_read_b32 v0, v3
	s_waitcnt lgkmcnt(0)
	v_readfirstlane_b32 s12, v0
	s_cmp_ge_u32 s12, s41
	s_mov_b64 s[4:5], -1
	s_cbranch_scc1 .LBB0_439
	s_lshr_b32 s98, s77, 8
	s_mul_i32 s98, s98, 0xe1
	s_lshr_b32 s98, s98, 14
	s_add_i32 s12, s12, s98
	s_cmp_ge_u32 s12, s41
	s_cbranch_scc1 .LBB0_440
	s_branch .Lq_have

.Lq_have:
	s_cmp_ge_u32 s12, s40
	s_cbranch_scc0 .LBB0_462
	v_mov_b64_e32 v[2:3], s[0:1]
	global_load_dwordx2 v[2:3], v[2:3], off offset:56
	s_sub_i32 s4, s12, s40
	s_lshr_b32 s5, s4, 9
	s_lshl_b32 s4, s4, 3
	v_mov_b32_e32 v151, v194
	s_and_b32 s13, s4, 0xff8
	s_mul_i32 s5, s5, s36
	v_bfe_u32 v0, v151, 3, 2
	v_cmp_gt_u32_e32 vcc, 32, v151
	v_or_b32_e32 v174, s13, v0
	v_mov_b32_e32 v0, 0x7f
	s_add_i32 s8, s5, s80
	v_cndmask_b32_e64 v170, 0, 1.0, vcc
	v_sub_co_u32_e32 v0, vcc, s13, v0
	s_ashr_i32 s9, s8, 31
	v_readfirstlane_b32 s4, v0
	s_lshl_b64 s[6:7], s[8:9], 12
	s_and_b32 s10, s4, 0xffffffe0
	s_and_b64 s[4:5], vcc, exec
	v_ashrrev_i32_e32 v4, 5, v151
	v_or_b32_e32 v175, 4, v174
	s_cselect_b32 s10, 0, s10
	s_or_b32 s14, s13, 7
	s_mov_b64 s[4:5], -1
	s_cmp_le_i32 s10, s14
	v_or_b32_e32 v146, s6, v175
	v_or_b32_e32 v148, s6, v174
	v_lshlrev_b32_e32 v172, 2, v4
	s_cbranch_scc0 .LBB0_459
	v_and_b32_e32 v5, 31, v151
	v_mov_b32_e32 v0, 0x1400000
	v_lshlrev_b32_e32 v6, 3, v4
	v_mad_i64_i32 v[8:9], s[4:5], s8, v0, v[154:155]
	v_mul_u32_u24_e32 v0, 0xa00, v5
	v_ashrrev_i32_e32 v7, 31, v6
	v_lshlrev_b32_e32 v0, 1, v0
	v_readlane_b32 s4, v255, 15
	v_lshl_add_u64 v[8:9], v[8:9], 0, v[0:1]
	v_lshlrev_b64 v[6:7], 1, v[6:7]
	v_readlane_b32 s5, v255, 16
	v_lshl_add_u64 v[152:153], v[8:9], 0, v[6:7]
	v_and_b32_e32 v10, 7, v151
	s_waitcnt vmcnt(0) lgkmcnt(0)
	v_lshl_add_u64 v[2:3], v[2:3], 0, s[4:5]
	v_mad_u64_u32 v[8:9], s[4:5], v146, s61, v[154:155]
	v_mad_i32_i24 v9, s7, v247, v9
	v_lshlrev_b32_e32 v0, 7, v10
	v_lshl_add_u64 v[8:9], v[8:9], 0, v[0:1]
	v_lshl_add_u64 v[8:9], v[8:9], 0, v[6:7]
	global_load_dwordx4 v[82:85], v[8:9], off offset:2656
	global_load_dwordx4 v[86:89], v[8:9], off offset:2624
	global_load_dwordx4 v[90:93], v[8:9], off offset:2592
	global_load_dwordx4 v[94:97], v[8:9], off offset:2560
	v_mad_u64_u32 v[8:9], s[4:5], v148, s61, v[154:155]
	v_mad_i32_i24 v9, s7, v247, v9
	v_lshl_add_u64 v[8:9], v[8:9], 0, v[0:1]
	v_lshlrev_b32_e32 v0, 2, v10
	v_lshl_add_u64 v[8:9], v[8:9], 0, v[6:7]
	v_lshl_add_u64 v[2:3], v[2:3], 0, v[0:1]
	global_load_dwordx4 v[98:101], v[8:9], off offset:2656
	global_load_dwordx4 v[102:105], v[8:9], off offset:2624
	global_load_dwordx4 v[106:109], v[8:9], off offset:2592
	global_load_dwordx4 v[110:113], v[8:9], off offset:2560
	s_mov_b32 s100, 0xf9800000
	s_mov_b32 s101, -1
	v_lshlrev_b32_e32 v140, 8, v146
	v_lshl_add_u32 v140, v6, 2, v140
	v_mov_b32_e32 v141, 0
	v_lshl_add_u64 v[140:141], v[154:155], 0, v[140:141]
	v_lshl_add_u64 v[140:141], v[140:141], 0, s[100:101]
	global_load_dwordx4 v[16:19], v[140:141], off offset:0
	global_load_dwordx4 v[20:23], v[140:141], off offset:16
	global_load_dwordx4 v[24:27], v[140:141], off offset:32
	global_load_dwordx4 v[28:31], v[140:141], off offset:48
	global_load_dwordx4 v[32:35], v[140:141], off offset:128
	global_load_dwordx4 v[36:39], v[140:141], off offset:144
	global_load_dwordx4 v[40:43], v[140:141], off offset:160
	global_load_dwordx4 v[44:47], v[140:141], off offset:176
	v_lshlrev_b32_e32 v140, 8, v148
	v_lshl_add_u32 v140, v6, 2, v140
	v_mov_b32_e32 v141, 0
	v_lshl_add_u64 v[140:141], v[154:155], 0, v[140:141]
	v_lshl_add_u64 v[140:141], v[140:141], 0, s[100:101]
	global_load_dwordx4 v[48:51], v[140:141], off offset:0
	global_load_dwordx4 v[52:55], v[140:141], off offset:16
	global_load_dwordx4 v[56:59], v[140:141], off offset:32
	global_load_dwordx4 v[60:63], v[140:141], off offset:48
	global_load_dwordx4 v[66:69], v[140:141], off offset:128
	global_load_dwordx4 v[70:73], v[140:141], off offset:144
	global_load_dwordx4 v[74:77], v[140:141], off offset:160
	global_load_dwordx4 v[78:81], v[140:141], off offset:176
	global_load_dword v0, v[2:3], off
	s_mul_i32 s4, s10, 0xa00
	s_ashr_i32 s5, s4, 31
	v_lshl_add_u64 v[2:3], s[4:5], 1, v[152:153]
	global_load_dwordx4 v[114:117], v[2:3], off offset:3680
	global_load_dwordx4 v[118:121], v[2:3], off offset:3648
	global_load_dwordx4 v[122:125], v[2:3], off offset:3616
	global_load_dwordx4 v[126:129], v[2:3], off offset:3584
	s_ashr_i32 s11, s10, 31
	s_lshl_b64 s[4:5], s[8:9], 19
	s_lshl_b64 s[8:9], s[10:11], 7
	s_add_u32 s4, s4, s8
	s_addc_u32 s5, s5, s9
	s_add_i32 s6, s13, 0xffffff87
	s_add_u32 s4, s4, 0x1000000
	s_addc_u32 s5, s5, 0
	v_mov_b32_e32 v14, v1
	v_mov_b32_e32 v15, v1
	v_lshlrev_b32_e32 v150, 2, v4
	v_mov_b32_e32 v4, v1
	v_mov_b32_e32 v8, v1
	v_mov_b32_e32 v9, v1
	v_mov_b32_e32 v10, v1
	v_mov_b32_e32 v11, v1
	v_mov_b32_e32 v12, v1
	v_mov_b32_e32 v13, v1
	v_mov_b32_e32 v147, s7
	v_mov_b32_e32 v149, s7
	v_add_u32_e32 v176, 0xffffff80, v174
	v_add_u32_e32 v177, 0xffffff84, v174
	v_mov_b32_e32 v171, v170
	v_mov_b32_e32 v173, v170
	s_waitcnt vmcnt(0) lgkmcnt(0)
	v_lshlrev_b32_e32 v130, 16, v94
	v_and_b32_e32 v131, 0xffff0000, v94
	v_lshlrev_b32_e32 v132, 16, v86
	v_and_b32_e32 v133, 0xffff0000, v86
	v_mul_f32_e32 v134, v17, v132
	v_mul_f32_e32 v135, v19, v133
	v_mul_f32_e32 v136, v16, v132
	v_mul_f32_e32 v137, v18, v133
	v_fma_f32 v134, v16, v130, -v134
	v_fma_f32 v135, v18, v131, -v135
	v_fma_f32 v136, v17, v130, v136
	v_fma_f32 v137, v19, v131, v137
	v_cvt_pk_bf16_f32 v94, v134, v135
	v_cvt_pk_bf16_f32 v86, v136, v137
	v_lshlrev_b32_e32 v130, 16, v95
	v_and_b32_e32 v131, 0xffff0000, v95
	v_lshlrev_b32_e32 v132, 16, v87
	v_and_b32_e32 v133, 0xffff0000, v87
	v_mul_f32_e32 v134, v21, v132
	v_mul_f32_e32 v135, v23, v133
	v_mul_f32_e32 v136, v20, v132
	v_mul_f32_e32 v137, v22, v133
	v_fma_f32 v134, v20, v130, -v134
	v_fma_f32 v135, v22, v131, -v135
	v_fma_f32 v136, v21, v130, v136
	v_fma_f32 v137, v23, v131, v137
	v_cvt_pk_bf16_f32 v95, v134, v135
	v_cvt_pk_bf16_f32 v87, v136, v137
	v_lshlrev_b32_e32 v130, 16, v96
	v_and_b32_e32 v131, 0xffff0000, v96
	v_lshlrev_b32_e32 v132, 16, v88
	v_and_b32_e32 v133, 0xffff0000, v88
	v_mul_f32_e32 v134, v25, v132
	v_mul_f32_e32 v135, v27, v133
	v_mul_f32_e32 v136, v24, v132
	v_mul_f32_e32 v137, v26, v133
	v_fma_f32 v134, v24, v130, -v134
	v_fma_f32 v135, v26, v131, -v135
	v_fma_f32 v136, v25, v130, v136
	v_fma_f32 v137, v27, v131, v137
	v_cvt_pk_bf16_f32 v96, v134, v135
	v_cvt_pk_bf16_f32 v88, v136, v137
	v_lshlrev_b32_e32 v130, 16, v97
	v_and_b32_e32 v131, 0xffff0000, v97
	v_lshlrev_b32_e32 v132, 16, v89
	v_and_b32_e32 v133, 0xffff0000, v89
	v_mul_f32_e32 v134, v29, v132
	v_mul_f32_e32 v135, v31, v133
	v_mul_f32_e32 v136, v28, v132
	v_mul_f32_e32 v137, v30, v133
	v_fma_f32 v134, v28, v130, -v134
	v_fma_f32 v135, v30, v131, -v135
	v_fma_f32 v136, v29, v130, v136
	v_fma_f32 v137, v31, v131, v137
	v_cvt_pk_bf16_f32 v97, v134, v135
	v_cvt_pk_bf16_f32 v89, v136, v137
	v_lshlrev_b32_e32 v130, 16, v90
	v_and_b32_e32 v131, 0xffff0000, v90
	v_lshlrev_b32_e32 v132, 16, v82
	v_and_b32_e32 v133, 0xffff0000, v82
	v_mul_f32_e32 v134, v33, v132
	v_mul_f32_e32 v135, v35, v133
	v_mul_f32_e32 v136, v32, v132
	v_mul_f32_e32 v137, v34, v133
	v_fma_f32 v134, v32, v130, -v134
	v_fma_f32 v135, v34, v131, -v135
	v_fma_f32 v136, v33, v130, v136
	v_fma_f32 v137, v35, v131, v137
	v_cvt_pk_bf16_f32 v90, v134, v135
	v_cvt_pk_bf16_f32 v82, v136, v137
	v_lshlrev_b32_e32 v130, 16, v91
	v_and_b32_e32 v131, 0xffff0000, v91
	v_lshlrev_b32_e32 v132, 16, v83
	v_and_b32_e32 v133, 0xffff0000, v83
	v_mul_f32_e32 v134, v37, v132
	v_mul_f32_e32 v135, v39, v133
	v_mul_f32_e32 v136, v36, v132
	v_mul_f32_e32 v137, v38, v133
	v_fma_f32 v134, v36, v130, -v134
	v_fma_f32 v135, v38, v131, -v135
	v_fma_f32 v136, v37, v130, v136
	v_fma_f32 v137, v39, v131, v137
	v_cvt_pk_bf16_f32 v91, v134, v135
	v_cvt_pk_bf16_f32 v83, v136, v137
	v_lshlrev_b32_e32 v130, 16, v92
	v_and_b32_e32 v131, 0xffff0000, v92
	v_lshlrev_b32_e32 v132, 16, v84
	v_and_b32_e32 v133, 0xffff0000, v84
	v_mul_f32_e32 v134, v41, v132
	v_mul_f32_e32 v135, v43, v133
	v_mul_f32_e32 v136, v40, v132
	v_mul_f32_e32 v137, v42, v133
	v_fma_f32 v134, v40, v130, -v134
	v_fma_f32 v135, v42, v131, -v135
	v_fma_f32 v136, v41, v130, v136
	v_fma_f32 v137, v43, v131, v137
	v_cvt_pk_bf16_f32 v92, v134, v135
	v_cvt_pk_bf16_f32 v84, v136, v137
	v_lshlrev_b32_e32 v130, 16, v93
	v_and_b32_e32 v131, 0xffff0000, v93
	v_lshlrev_b32_e32 v132, 16, v85
	v_and_b32_e32 v133, 0xffff0000, v85
	v_mul_f32_e32 v134, v45, v132
	v_mul_f32_e32 v135, v47, v133
	v_mul_f32_e32 v136, v44, v132
	v_mul_f32_e32 v137, v46, v133
	v_fma_f32 v134, v44, v130, -v134
	v_fma_f32 v135, v46, v131, -v135
	v_fma_f32 v136, v45, v130, v136
	v_fma_f32 v137, v47, v131, v137
	v_cvt_pk_bf16_f32 v93, v134, v135
	v_cvt_pk_bf16_f32 v85, v136, v137
	v_lshlrev_b32_e32 v130, 16, v110
	v_and_b32_e32 v131, 0xffff0000, v110
	v_lshlrev_b32_e32 v132, 16, v102
	v_and_b32_e32 v133, 0xffff0000, v102
	v_mul_f32_e32 v134, v49, v132
	v_mul_f32_e32 v135, v51, v133
	v_mul_f32_e32 v136, v48, v132
	v_mul_f32_e32 v137, v50, v133
	v_fma_f32 v134, v48, v130, -v134
	v_fma_f32 v135, v50, v131, -v135
	v_fma_f32 v136, v49, v130, v136
	v_fma_f32 v137, v51, v131, v137
	v_cvt_pk_bf16_f32 v110, v134, v135
	v_cvt_pk_bf16_f32 v102, v136, v137
	v_lshlrev_b32_e32 v130, 16, v111
	v_and_b32_e32 v131, 0xffff0000, v111
	v_lshlrev_b32_e32 v132, 16, v103
	v_and_b32_e32 v133, 0xffff0000, v103
	v_mul_f32_e32 v134, v53, v132
	v_mul_f32_e32 v135, v55, v133
	v_mul_f32_e32 v136, v52, v132
	v_mul_f32_e32 v137, v54, v133
	v_fma_f32 v134, v52, v130, -v134
	v_fma_f32 v135, v54, v131, -v135
	v_fma_f32 v136, v53, v130, v136
	v_fma_f32 v137, v55, v131, v137
	v_cvt_pk_bf16_f32 v111, v134, v135
	v_cvt_pk_bf16_f32 v103, v136, v137
	v_lshlrev_b32_e32 v130, 16, v112
	v_and_b32_e32 v131, 0xffff0000, v112
	v_lshlrev_b32_e32 v132, 16, v104
	v_and_b32_e32 v133, 0xffff0000, v104
	v_mul_f32_e32 v134, v57, v132
	v_mul_f32_e32 v135, v59, v133
	v_mul_f32_e32 v136, v56, v132
	v_mul_f32_e32 v137, v58, v133
	v_fma_f32 v134, v56, v130, -v134
	v_fma_f32 v135, v58, v131, -v135
	v_fma_f32 v136, v57, v130, v136
	v_fma_f32 v137, v59, v131, v137
	v_cvt_pk_bf16_f32 v112, v134, v135
	v_cvt_pk_bf16_f32 v104, v136, v137
	v_lshlrev_b32_e32 v130, 16, v113
	v_and_b32_e32 v131, 0xffff0000, v113
	v_lshlrev_b32_e32 v132, 16, v105
	v_and_b32_e32 v133, 0xffff0000, v105
	v_mul_f32_e32 v134, v61, v132
	v_mul_f32_e32 v135, v63, v133
	v_mul_f32_e32 v136, v60, v132
	v_mul_f32_e32 v137, v62, v133
	v_fma_f32 v134, v60, v130, -v134
	v_fma_f32 v135, v62, v131, -v135
	v_fma_f32 v136, v61, v130, v136
	v_fma_f32 v137, v63, v131, v137
	v_cvt_pk_bf16_f32 v113, v134, v135
	v_cvt_pk_bf16_f32 v105, v136, v137
	v_lshlrev_b32_e32 v130, 16, v106
	v_and_b32_e32 v131, 0xffff0000, v106
	v_lshlrev_b32_e32 v132, 16, v98
	v_and_b32_e32 v133, 0xffff0000, v98
	v_mul_f32_e32 v134, v67, v132
	v_mul_f32_e32 v135, v69, v133
	v_mul_f32_e32 v136, v66, v132
	v_mul_f32_e32 v137, v68, v133
	v_fma_f32 v134, v66, v130, -v134
	v_fma_f32 v135, v68, v131, -v135
	v_fma_f32 v136, v67, v130, v136
	v_fma_f32 v137, v69, v131, v137
	v_cvt_pk_bf16_f32 v106, v134, v135
	v_cvt_pk_bf16_f32 v98, v136, v137
	v_lshlrev_b32_e32 v130, 16, v107
	v_and_b32_e32 v131, 0xffff0000, v107
	v_lshlrev_b32_e32 v132, 16, v99
	v_and_b32_e32 v133, 0xffff0000, v99
	v_mul_f32_e32 v134, v71, v132
	v_mul_f32_e32 v135, v73, v133
	v_mul_f32_e32 v136, v70, v132
	v_mul_f32_e32 v137, v72, v133
	v_fma_f32 v134, v70, v130, -v134
	v_fma_f32 v135, v72, v131, -v135
	v_fma_f32 v136, v71, v130, v136
	v_fma_f32 v137, v73, v131, v137
	v_cvt_pk_bf16_f32 v107, v134, v135
	v_cvt_pk_bf16_f32 v99, v136, v137
	v_lshlrev_b32_e32 v130, 16, v108
	v_and_b32_e32 v131, 0xffff0000, v108
	v_lshlrev_b32_e32 v132, 16, v100
	v_and_b32_e32 v133, 0xffff0000, v100
	v_mul_f32_e32 v134, v75, v132
	v_mul_f32_e32 v135, v77, v133
	v_mul_f32_e32 v136, v74, v132
	v_mul_f32_e32 v137, v76, v133
	v_fma_f32 v134, v74, v130, -v134
	v_fma_f32 v135, v76, v131, -v135
	v_fma_f32 v136, v75, v130, v136
	v_fma_f32 v137, v77, v131, v137
	v_cvt_pk_bf16_f32 v108, v134, v135
	v_cvt_pk_bf16_f32 v100, v136, v137
	v_lshlrev_b32_e32 v130, 16, v109
	v_and_b32_e32 v131, 0xffff0000, v109
	v_lshlrev_b32_e32 v132, 16, v101
	v_and_b32_e32 v133, 0xffff0000, v101
	v_mul_f32_e32 v134, v79, v132
	v_mul_f32_e32 v135, v81, v133
	v_mul_f32_e32 v136, v78, v132
	v_mul_f32_e32 v137, v80, v133
	v_fma_f32 v134, v78, v130, -v134
	v_fma_f32 v135, v80, v131, -v135
	v_fma_f32 v136, v79, v130, v136
	v_fma_f32 v137, v81, v131, v137
	v_cvt_pk_bf16_f32 v109, v134, v135
	v_cvt_pk_bf16_f32 v101, v136, v137
	v_mul_f32_e32 v178, 0x3fb8aa3b, v0
	v_lshlrev_b32_e32 v0, 5, v5
	v_lshl_add_u64 v[2:3], s[4:5], 0, v[0:1]
	v_lshl_add_u64 v[2:3], v[2:3], 0, v[6:7]
	v_lshl_add_u64 v[168:169], v[164:165], 0, v[2:3]
	v_mov_b32_e32 v0, v1
	v_mov_b32_e32 v2, v1
	v_mov_b32_e32 v3, v1
	v_mov_b32_e32 v5, v1
	v_mov_b32_e32 v6, v1
	v_mov_b32_e32 v7, v1
	v_mov_b64_e32 v[64:65], v[14:15]
	v_mov_b64_e32 v[48:49], v[14:15]
	v_mov_b64_e32 v[32:33], v[14:15]
	v_mov_b64_e32 v[62:63], v[12:13]
	v_mov_b64_e32 v[60:61], v[10:11]
	v_mov_b64_e32 v[58:59], v[8:9]
	v_mov_b64_e32 v[56:57], v[6:7]
	v_mov_b64_e32 v[54:55], v[4:5]
	v_mov_b64_e32 v[52:53], v[2:3]
	v_mov_b64_e32 v[50:51], v[0:1]
	v_mov_b64_e32 v[46:47], v[12:13]
	v_mov_b64_e32 v[44:45], v[10:11]
	v_mov_b64_e32 v[42:43], v[8:9]
	v_mov_b64_e32 v[40:41], v[6:7]
	v_mov_b64_e32 v[38:39], v[4:5]
	v_mov_b64_e32 v[36:37], v[2:3]
	v_mov_b64_e32 v[34:35], v[0:1]
	v_mov_b64_e32 v[30:31], v[12:13]
	v_mov_b64_e32 v[28:29], v[10:11]
	v_mov_b64_e32 v[26:27], v[8:9]
	v_mov_b64_e32 v[24:25], v[6:7]
	v_mov_b64_e32 v[22:23], v[4:5]
	v_mov_b64_e32 v[20:21], v[2:3]
	v_mov_b64_e32 v[18:19], v[0:1]
	v_mov_b64_e32 v[16:17], v[14:15]
	v_mov_b64_e32 v[14:15], v[12:13]
	v_mov_b64_e32 v[12:13], v[10:11]
	v_mov_b64_e32 v[10:11], v[8:9]
	v_mov_b64_e32 v[8:9], v[6:7]
	v_mov_b64_e32 v[6:7], v[4:5]
	v_mov_b64_e32 v[4:5], v[2:3]
	v_mov_b64_e32 v[2:3], v[0:1]
	v_mov_b32_e32 v195, v178
